# decode out-proj starts after the delta-rule iterations and waits for the mLSTM ones before K>=1024 (two-stage wait), on top of the re-dealt schedule
# baseline (speedup 1.0000x reference)
.LBB0_89:
	v_or_b32_e32 v0, s2, v6
	v_cmp_eq_u32_e32 vcc, 0, v0
	s_and_saveexec_b64 s[0:1], vcc
	s_cbranch_execz .LBB0_91
	v_mov_b32_e32 v0, 0x17feb000
	v_mov_b32_e32 v1, 0
	v_mov_b32_e32 v2, 0x1000
	global_store_dword v0, v2, s[30:31]
	global_store_dword v0, v1, s[30:31] offset:128
	global_store_dword v0, v1, s[30:31] offset:192
	global_store_dword v0, v1, s[30:31] offset:64

.LBB0_556:
	s_cmp_lt_u32 s2, 0xc0
	s_cbranch_scc1 .Lsd_skip
	s_cmpk_gt_i32 s44, 0xff
	s_cbranch_scc1 .Lsd_skip
	s_waitcnt vmcnt(0)
	s_barrier
	s_mov_b64 s[4:5], exec
	v_readlane_b32 s6, v239, 4
	v_readlane_b32 s7, v239, 5
	s_and_b64 s[6:7], s[4:5], s[6:7]
	s_mov_b64 exec, s[6:7]
	s_cbranch_execz .Lsd_done
	buffer_wbl2 sc1
	s_waitcnt vmcnt(0)
	v_mov_b32_e32 v0, 0x17feb040
	v_mov_b32_e32 v1, 1
	global_atomic_add v0, v1, s[30:31]
.Lsd_done:
	s_mov_b64 exec, s[4:5]

.LBB0_618:
	s_waitcnt vmcnt(0)
	s_add_u32 s20, s30, 0x17feb0c0
	s_addc_u32 s21, s31, 0
	s_barrier
	s_mov_b64 s[4:5], exec
	v_readlane_b32 s6, v239, 4
	v_readlane_b32 s7, v239, 5
	s_and_b64 s[6:7], s[4:5], s[6:7]
	v_readlane_b32 s68, v238, 27
	v_readlane_b32 s69, v238, 28
	s_mov_b64 exec, s[6:7]
	s_cbranch_execz .LBB0_635
	s_mov_b64 s[6:7], exec
	buffer_wbl2 sc1
	s_waitcnt vmcnt(0)
	s_waitcnt vmcnt(0)
	v_mbcnt_lo_u32_b32 v0, s6, 0
	v_mbcnt_hi_u32_b32 v0, s7, v0
	v_cmp_eq_u32_e32 vcc, 0, v0
	s_and_saveexec_b64 s[8:9], vcc
	s_cbranch_execz .LBB0_621
	s_bcnt1_i32_b64 s6, s[6:7]
	v_mov_b32_e32 v0, 0
	v_mov_b32_e32 v1, s6
	global_atomic_add v0, v1, s[20:21]
	s_cmp_lt_u32 s2, 0x60
	s_cbranch_scc1 .Lsd2_skip
	s_cmp_ge_u32 s2, 0xc0
	s_cbranch_scc1 .Lsd2_skip
	global_atomic_add v0, v1, s[20:21] offset:-128
.Lsd2_skip:
.LBB0_621:
	s_or_b64 exec, exec, s[8:9]
	s_add_u32 s6, s30, 0x17feb080
	s_addc_u32 s7, s31, 0
	s_mov_b32 s10, 0x100000
	v_mov_b32_e32 v0, 0
	s_branch .LBB0_624

.LBB0_662:
	s_sub_i32 s68, s2, 32
	v_readlane_b32 s16, v239, 2
	s_nop 0
	s_sub_i32 s16, s16, 32
	v_readlane_b32 s4, v238, 31
	v_readlane_b32 s5, v238, 32
	s_and_b64 s[4:5], s[4:5], exec
	s_cselect_b32 s8, 0xc0, 64
	s_cmp_ge_i32 s68, s8
	s_cselect_b64 s[4:5], -1, 0
	s_or_b32 s6, s8, 32
	s_cmp_lt_i32 s68, s6
	s_cselect_b64 s[6:7], -1, 0
	s_and_b64 s[4:5], s[4:5], s[6:7]
	s_and_b64 vcc, exec, s[4:5]
	s_cbranch_vccz .LBB0_701
	s_mov_b64 s[4:5], exec
	v_readlane_b32 s6, v239, 4
	v_readlane_b32 s7, v239, 5
	s_and_b64 s[6:7], s[4:5], s[6:7]
	s_mov_b64 exec, s[6:7]
	s_cbranch_execz .LBB0_678
	s_mov_b32 s9, 0x100000
	s_sub_u32 s20, s20, 0x80
	s_subb_u32 s21, s21, 0
	s_movk_i32 s16, 0xa0
	v_mov_b32_e32 v0, 0
	s_branch .LBB0_667

.LBB0_681:
	s_cmp_lg_u32 s36, 14
	s_cbranch_scc1 .Lkw_skip
	v_readlane_b32 vcc_lo, v239, 4
	v_readlane_b32 vcc_hi, v239, 5
	s_nop 1
	s_mov_b64 exec, vcc
	s_cbranch_execz .Lkw_done
	v_mov_b32_e32 v240, s30
	v_mov_b32_e32 v241, s31
	v_add_co_u32_e32 v240, vcc, 0x17feb0c0, v240
	s_nop 1
	v_addc_co_u32_e32 v241, vcc, 0, v241, vcc
	v_mov_b32_e32 v243, 0
.Lkw_poll:
	global_load_dword v242, v[240:241], off sc1
	s_waitcnt vmcnt(0)
	v_cmp_le_u32_e32 vcc, 0xe0, v242
	s_cbranch_vccnz .Lkw_ok
	s_sleep 2
	v_add_u32_e32 v243, 1, v243
	v_cmp_lt_u32_e32 vcc, 0x200000, v243
	s_cbranch_vccnz .Lkw_ok
	s_branch .Lkw_poll
